# attention: s_setprio 1 raised before the cvt_pk block at the end of the softmax segment (was at start of MFMA segment)
# speedup vs baseline: 1.0161x; 1.0063x over previous
; #define SBAR() __builtin_amdgcn_sched_barrier(0)
; __device__ __forceinline__ unsigned cvtpk(float lo, float hi) { unsigned r; asm volatile("v_cvt_pk_bf16_f32 %0, %1, %2" : "=v"(r) : "v"(lo), "v"(hi)); return r; }
; #define ABAR() asm volatile("s_waitcnt lgkmcnt(0)\n\ts_barrier" ::: "memory")
; __device__ __forceinline__ void finishSM(f32x4a (&s)[4][2], float& l0, float& l1, bf16x8 (&pa)[2][2]) {
; #pragma unroll
;   for (int kb = 0; kb < 4; ++kb)
; #pragma unroll
;     for (int qb = 0; qb < 2; ++qb)
; #pragma unroll
;       for (int e = 0; e < 4; ++e) s[kb][qb][e] = __builtin_amdgcn_exp2f(s[kb][qb][e]);
;   float a0 = 0.f, a1 = 0.f, a2 = 0.f, a3 = 0.f, b0 = 0.f, b1 = 0.f, b2 = 0.f, b3 = 0.f;
; #pragma unroll
;   for (int kb = 0; kb < 4; ++kb) { a0 += s[kb][0][0]; a1 += s[kb][0][1]; a2 += s[kb][0][2]; a3 += s[kb][0][3]; b0 += s[kb][1][0]; b1 += s[kb][1][1]; b2 += s[kb][1][2]; b3 += s[kb][1][3]; }
;   l0 += (a0 + a1) + (a2 + a3); l1 += (b0 + b1) + (b2 + b3);
; #pragma unroll
;   for (int qb = 0; qb < 2; ++qb)
; #pragma unroll
;     for (int st = 0; st < 2; ++st) { u32x4 w = {cvtpk(s[2 * st][qb][0], s[2 * st][qb][1]), cvtpk(s[2 * st][qb][2], s[2 * st][qb][3]), cvtpk(s[2 * st + 1][qb][0], s[2 * st + 1][qb][1]), cvtpk(s[2 * st + 1][qb][2], s[2 * st + 1][qb][3])};
;       pa[qb][st] = *reinterpret_cast<bf16x8*>(&w); }
; __device__ __forceinline__ void attn_unit(int h, int qb_, const Tensors& T, char* lds, LASP unsigned char* ldsl, int tid_in) {
;     ...
;       if (hf) { asm volatile("s_waitcnt vmcnt(6)" ::: "memory"); ABAR(); }
;       { const int vbt = vb0 + sgv * STGB; const int sgk = sgv == NSTG - 1 ? 0 : sgv + 1; __builtin_amdgcn_s_setprio(1);
;         vread<0>(va, vbt); SBAR();
.LBB0_571:
	v_exp_f32_e32 v195, v56
	v_exp_f32_e32 v193, v57
	v_exp_f32_e32 v191, v58
	v_exp_f32_e32 v187, v59
	v_exp_f32_e32 v194, v60
	v_exp_f32_e32 v192, v61
	v_exp_f32_e32 v190, v62
	v_exp_f32_e32 v186, v63
	v_exp_f32_e32 v189, v64
	v_exp_f32_e32 v185, v65
	v_exp_f32_e32 v175, v66
	v_exp_f32_e32 v171, v67
	v_exp_f32_e32 v188, v68
	v_exp_f32_e32 v184, v69
	v_exp_f32_e32 v174, v70
	v_exp_f32_e32 v170, v71
	v_exp_f32_e32 v173, v80
	v_exp_f32_e32 v169, v81
	v_exp_f32_e32 v167, v82
	v_exp_f32_e32 v163, v83
	v_exp_f32_e32 v172, v88
	v_exp_f32_e32 v168, v89
	v_exp_f32_e32 v166, v90
	v_exp_f32_e32 v162, v91
	v_exp_f32_e32 v165, v92
	v_exp_f32_e32 v161, v93
	v_exp_f32_e32 v159, v94
	v_exp_f32_e32 v157, v95
	v_exp_f32_e32 v164, v96
	v_exp_f32_e32 v160, v97
	v_exp_f32_e32 v158, v98
	v_exp_f32_e32 v156, v99
	s_setprio 1
	s_andn2_b64 vcc, exec, s[40:41]
	v_cvt_pk_bf16_f32 v116, v195, v193
	v_cvt_pk_bf16_f32 v117, v191, v187
	v_cvt_pk_bf16_f32 v118, v189, v185
	v_cvt_pk_bf16_f32 v119, v175, v171
	v_cvt_pk_bf16_f32 v112, v173, v169
	v_cvt_pk_bf16_f32 v113, v167, v163
	v_cvt_pk_bf16_f32 v114, v165, v161
	v_cvt_pk_bf16_f32 v115, v159, v157
	v_cvt_pk_bf16_f32 v124, v194, v192
	v_cvt_pk_bf16_f32 v125, v190, v186
	v_cvt_pk_bf16_f32 v126, v188, v184
	v_cvt_pk_bf16_f32 v127, v174, v170
	v_cvt_pk_bf16_f32 v120, v172, v168
	v_cvt_pk_bf16_f32 v121, v166, v162
	v_cvt_pk_bf16_f32 v122, v164, v160
	v_cvt_pk_bf16_f32 v123, v158, v156
	s_cbranch_vccnz .LBB0_573
	s_waitcnt vmcnt(6)
	s_waitcnt lgkmcnt(0)
	s_barrier
.LBB0_573:
	s_mul_i32 s4, s43, 0x6000
	v_add_u32_e32 v238, s4, v232
	s_add_i32 s4, s43, 1
	s_cmp_lg_u32 s43, 5
	s_cselect_b32 s43, s4, 0
	ds_read_b64_tr_b16 v[136:137], v238 offset:0
	ds_read_b64_tr_b16 v[138:139], v238 offset:0x200
	ds_read_b64_tr_b16 v[128:129], v238 offset:0x400
	ds_read_b64_tr_b16 v[130:131], v238 offset:0x600
	ds_read_b64_tr_b16 v[140:141], v238 offset:0x800
	ds_read_b64_tr_b16 v[142:143], v238 offset:0xa00
	ds_read_b64_tr_b16 v[132:133], v238 offset:0xc00
	ds_read_b64_tr_b16 v[134:135], v238 offset:0xe00
	s_cmpk_eq_i32 s44, 0xff
	s_cbranch_scc1 .LBB0_575
	s_mul_i32 s4, s43, 0x6000
	s_add_i32 s4, s4, 0
	v_add_u32_e32 v178, s4, v205
	v_add_u32_e32 v179, s4, v206
	ds_read_b128 v[56:59], v178
	ds_read_b128 v[60:63], v178 offset:2048
	ds_read_b128 v[64:67], v179
	ds_read_b128 v[68:71], v179 offset:2048
	s_waitcnt lgkmcnt(0)
	v_mfma_f32_16x16x32_bf16 v[80:83], v[56:59], v[4:7], 0
	v_add_f32_e32 v188, v188, v194
	v_add_f32_e32 v189, v189, v195
	v_mfma_f32_16x16x32_bf16 v[88:91], v[56:59], v[12:15], 0
	v_add_f32_e32 v184, v184, v192
	v_add_f32_e32 v185, v185, v193
	v_mfma_f32_16x16x32_bf16 v[92:95], v[60:63], v[4:7], 0
	v_add_f32_e32 v174, v174, v190
	v_add_f32_e32 v175, v175, v191
	v_mfma_f32_16x16x32_bf16 v[96:99], v[60:63], v[12:15], 0
	v_add_f32_e32 v170, v170, v186
	v_add_f32_e32 v171, v171, v187
	v_mfma_f32_16x16x32_bf16 v[56:59], v[64:67], v[8:11], v[80:83]
	v_add_f32_e32 v172, v172, v188
	v_add_f32_e32 v173, v173, v189
	v_mfma_f32_16x16x32_bf16 v[60:63], v[64:67], v[16:19], v[88:91]
	v_add_f32_e32 v168, v168, v184
	v_add_f32_e32 v169, v169, v185
	v_mfma_f32_16x16x32_bf16 v[64:67], v[68:71], v[8:11], v[92:95]
	v_add_f32_e32 v166, v166, v174
	v_add_f32_e32 v167, v167, v175
	v_mfma_f32_16x16x32_bf16 v[68:71], v[68:71], v[16:19], v[96:99]
	v_add_f32_e32 v162, v162, v170
	v_add_f32_e32 v163, v163, v171
	s_nop 0
	ds_read_b128 v[80:83], v178 offset:4096
	ds_read_b128 v[88:91], v178 offset:6144
	ds_read_b128 v[92:95], v179 offset:4096
	ds_read_b128 v[96:99], v179 offset:6144
	s_waitcnt lgkmcnt(3)
	v_mfma_f32_16x16x32_bf16 v[240:243], v[80:83], v[4:7], 0
	v_add_f32_e32 v164, v164, v172
	v_add_f32_e32 v165, v165, v173
	v_mfma_f32_16x16x32_bf16 v[244:247], v[80:83], v[12:15], 0
	v_add_f32_e32 v160, v160, v168
	v_add_f32_e32 v161, v161, v169
	s_waitcnt lgkmcnt(2)
	v_mfma_f32_16x16x32_bf16 v[248:251], v[88:91], v[4:7], 0
	v_add_f32_e32 v158, v158, v166
	v_add_f32_e32 v159, v159, v167
	v_mfma_f32_16x16x32_bf16 v[228:231], v[88:91], v[12:15], 0
	v_add_f32_e32 v156, v156, v162
	v_add_f32_e32 v157, v157, v163
	s_waitcnt lgkmcnt(1)
	v_mfma_f32_16x16x32_bf16 v[80:83], v[92:95], v[8:11], v[240:243]
	v_add_f32_e32 v160, v164, v160
	v_add_f32_e32 v161, v165, v161
	v_mfma_f32_16x16x32_bf16 v[88:91], v[92:95], v[16:19], v[244:247]
	v_add_f32_e32 v156, v158, v156
	v_add_f32_e32 v157, v159, v157
	s_waitcnt lgkmcnt(0)
	v_mfma_f32_16x16x32_bf16 v[92:95], v[96:99], v[8:11], v[248:251]
	v_add_f32_e32 v156, v160, v156
	v_add_f32_e32 v157, v161, v157
	v_mfma_f32_16x16x32_bf16 v[96:99], v[96:99], v[16:19], v[228:231]
	v_add_f32_e32 v154, v154, v156
	v_add_f32_e32 v155, v155, v157
	s_branch .LBB0_576
